# v12dma
# speedup vs baseline: 1.0501x; 1.0299x over previous
; #define SBAR() __builtin_amdgcn_sched_barrier(0)
; #define SLOAD(i, k0) do { sr_[i].vs0 = *reinterpret_cast<const bf16x8*>(&Vh[(size_t)((k0) + sr) * ldk + sc]); sr_[i].vs1 = *reinterpret_cast<const bf16x8*>(&Vh[(size_t)((k0) + 32 + sr) * ldk + sc]); \
;     sr_[i].ks0 = *reinterpret_cast<const bf16x8*>(&Kh[(size_t)((k0) + sr) * ldk + sc]); sr_[i].ks1 = *reinterpret_cast<const bf16x8*>(&Kh[(size_t)((k0) + 32 + sr) * ldk + sc]); } while (0)
; #define SWRITE(b, i) do { *(bf16x8*)((char*)V_lds + (b) * SHM_V + vst0) = sr_[i].vs0;          \
;     *(bf16x8*)((char*)V_lds + (b) * SHM_V + vst1) = sr_[i].vs1; int kc = sc * 2;               \
;     *(bf16x8*)((char*)K_lds + (b) * SHM_K + KSWZ(sr, kc)) = sr_[i].ks0;                       \
;     *(bf16x8*)((char*)K_lds + (b) * SHM_K + KSWZ(32 + sr, kc)) = sr_[i].ks1; } while (0)
; #define SWAIT() asm volatile("s_waitcnt vmcnt(4)" ::: "memory")
; template <bool DIFF, bool FAST> ...
;     ...
;   for (int j = 1; j + 1 < NT; j += 2) {
;     SBAR(); qkt<ND0>(pB0, pB1, (bf16*)((char*)K_lds + SHM_K), qr, r32, hi, colbase);
;     finishSM_bal(pA1, psA, l_reg, pa2, pa3); SBAR();
;     SLOAD(SO, (j + 2) * KVBLK); SBAR();
;     pv_d0(o, vb0, paA0, paA1, pa2, pa3); partialSM_bal(pB0, psB, paB0, paB1);
;     __syncthreads(); SWAIT(); SWRITE(0, SE);
.LBB0_564:
	v_readfirstlane_b32 vcc_lo, v217
	s_lshr_b32 vcc_lo, vcc_lo, 6
	s_lshl_b32 vcc_lo, vcc_lo, 10
	s_mov_b32 vcc_hi, 0x10000
	v_lshrrev_b32_e32 v233, 4, v217
	v_and_b32_e32 v220, 15, v233
	v_xor_b32_e32 v220, v220, v217
	v_and_b32_e32 v220, 15, v220
	v_lshlrev_b32_e32 v233, 9, v233
	v_lshl_add_u32 v233, v220, 4, v233
	v_bfe_u32 v218, v217, 2, 2
	v_bfe_u32 v220, v217, 7, 1
	v_lshl_or_b32 v218, v220, 2, v218
	v_bfe_u32 v220, v217, 4, 1
	v_lshl_or_b32 v218, v220, 3, v218
	v_bfe_u32 v220, v217, 8, 1
	v_lshl_or_b32 v218, v220, 4, v218
	v_lshlrev_b32_e32 v218, 9, v218
	v_and_b32_e32 v220, 3, v217
	v_lshl_or_b32 v218, v220, 4, v218
	v_bfe_u32 v220, v217, 5, 2
	v_lshl_or_b32 v218, v220, 6, v218
	s_waitcnt vmcnt(0)
.Lattn_gqa_top:
	ds_read_b128 v[80:83], v224 offset:49152
	ds_read_b128 v[84:87], v224 offset:57344
	ds_read_b128 v[170:173], v225 offset:49152
	ds_read_b128 v[174:177], v225 offset:57344
	ds_read_b128 v[178:181], v226 offset:49152
	ds_read_b128 v[234:237], v226 offset:57344
	ds_read_b128 v[238:241], v227 offset:49152
	ds_read_b128 v[242:245], v227 offset:57344
	s_add_i32 s9, s7, -2
	s_lshl_b32 s9, s9, 15
	s_add_u32 s26, s10, s9
	s_addc_u32 s27, s11, 0
	s_add_u32 m0, vcc_lo, vcc_hi
	s_nop 0
	global_load_lds_dwordx4 v218, s[26:27]
	v_exp_f32_e32 v64, v64
	v_exp_f32_e32 v65, v65
	s_waitcnt lgkmcnt(7)
	v_mfma_f32_32x32x16_bf16 v[96:111], v[80:83], v[142:145], 0
	s_add_u32 s26, s26, 0x4000
	s_addc_u32 s27, s27, 0
	s_add_u32 m0, m0, 0x2000
	s_nop 0
	global_load_lds_dwordx4 v218, s[26:27]
	v_exp_f32_e32 v66, v66
	v_exp_f32_e32 v67, v67
	s_waitcnt lgkmcnt(6)
	v_mfma_f32_32x32x16_bf16 v[80:95], v[84:87], v[142:145], 0
	s_add_u32 s26, s28, s9
	s_addc_u32 s27, s29, 0
	s_add_u32 m0, vcc_lo, 0x8000
	s_nop 0
	global_load_lds_dwordx4 v233, s[26:27]
	v_exp_f32_e32 v68, v68
	v_exp_f32_e32 v69, v69
	s_waitcnt lgkmcnt(5)
	v_mfma_f32_32x32x16_bf16 v[96:111], v[170:173], v[138:141], v[96:111]
	ds_read_b128 v[170:173], v228 offset:49152
	s_add_u32 s26, s26, 0x4000
	s_addc_u32 s27, s27, 0
	s_add_u32 m0, m0, 0x2000
	s_nop 0
	global_load_lds_dwordx4 v233, s[26:27]
	v_exp_f32_e32 v70, v70
	v_exp_f32_e32 v71, v71
	s_waitcnt lgkmcnt(5)
	v_mfma_f32_32x32x16_bf16 v[80:95], v[174:177], v[138:141], v[80:95]
	ds_read_b128 v[174:177], v228 offset:57344
	v_exp_f32_e32 v72, v72
	v_exp_f32_e32 v73, v73
	s_waitcnt lgkmcnt(5)
	v_mfma_f32_32x32x16_bf16 v[96:111], v[178:181], v[134:137], v[96:111]
	ds_read_b128 v[178:181], v229 offset:49152
	v_exp_f32_e32 v74, v74
	v_exp_f32_e32 v75, v75
	s_waitcnt lgkmcnt(5)
	v_mfma_f32_32x32x16_bf16 v[80:95], v[234:237], v[134:137], v[80:95]
	ds_read_b128 v[234:237], v229 offset:57344
	v_exp_f32_e32 v76, v76
	v_exp_f32_e32 v77, v77
	s_waitcnt lgkmcnt(5)
	v_mfma_f32_32x32x16_bf16 v[96:111], v[238:241], v[130:133], v[96:111]
	ds_read_b128 v[238:241], v231 offset:49152
	v_exp_f32_e32 v78, v78
	v_exp_f32_e32 v79, v79
	s_waitcnt lgkmcnt(5)
	v_mfma_f32_32x32x16_bf16 v[80:95], v[242:245], v[130:133], v[80:95]
	ds_read_b128 v[242:245], v231 offset:57344
	v_add_f32_e32 v197, v194, v64
	v_add_f32_e32 v197, v65, v197
	v_add_f32_e32 v197, v66, v197
	v_add_f32_e32 v197, v67, v197
	s_waitcnt lgkmcnt(5)
	v_mfma_f32_32x32x16_bf16 v[96:111], v[170:173], v[126:129], v[96:111]
	ds_read_b128 v[170:173], v230 offset:49152
	v_add_f32_e32 v197, v68, v197
	v_add_f32_e32 v197, v69, v197
	v_add_f32_e32 v197, v70, v197
	v_add_f32_e32 v197, v71, v197
	s_waitcnt lgkmcnt(5)
	v_mfma_f32_32x32x16_bf16 v[80:95], v[174:177], v[126:129], v[80:95]
	ds_read_b128 v[174:177], v230 offset:57344
	v_add_f32_e32 v197, v72, v197
	v_add_f32_e32 v197, v73, v197
	v_add_f32_e32 v197, v74, v197
	v_add_f32_e32 v197, v75, v197
	s_waitcnt lgkmcnt(5)
	v_mfma_f32_32x32x16_bf16 v[96:111], v[178:181], v[122:125], v[96:111]
	v_add_f32_e32 v197, v76, v197
	v_add_f32_e32 v197, v77, v197
	v_add_f32_e32 v197, v78, v197
	v_add_f32_e32 v197, v79, v197
	s_waitcnt lgkmcnt(4)
	v_mfma_f32_32x32x16_bf16 v[80:95], v[234:237], v[122:125], v[80:95]
	v_cvt_pk_bf16_f32 v64, v64, v65
	v_cvt_pk_bf16_f32 v65, v66, v67
	v_cvt_pk_bf16_f32 v66, v68, v69
	v_cvt_pk_bf16_f32 v67, v70, v71
	s_waitcnt lgkmcnt(3)
	v_mfma_f32_32x32x16_bf16 v[96:111], v[238:241], v[118:121], v[96:111]
	v_cvt_pk_bf16_f32 v68, v72, v73
	v_cvt_pk_bf16_f32 v69, v74, v75
	v_cvt_pk_bf16_f32 v70, v76, v77
	v_cvt_pk_bf16_f32 v71, v78, v79
	s_waitcnt lgkmcnt(2)
	v_mfma_f32_32x32x16_bf16 v[80:95], v[242:245], v[118:121], v[80:95]
	v_mov_b32_e32 v195, v197
	v_permlane32_swap_b32_e32 v64, v66
	v_permlane32_swap_b32_e32 v65, v67
	v_permlane32_swap_b32_e32 v68, v70
	s_waitcnt lgkmcnt(1)
	v_mfma_f32_32x32x16_bf16 v[96:111], v[170:173], v[114:117], v[96:111]
	v_permlane32_swap_b32_e32 v69, v71
	v_permlane32_swap_b32_e32 v197, v195
	s_waitcnt lgkmcnt(0)
	v_mfma_f32_32x32x16_bf16 v[80:95], v[174:177], v[114:117], v[80:95]
	ds_read_b64_tr_b16 v[72:73], v191 offset:0
	ds_read_b64_tr_b16 v[74:75], v191 offset:0x800
	ds_read_b64_tr_b16 v[76:77], v191 offset:0x1000
	ds_read_b64_tr_b16 v[78:79], v191 offset:0x1800
	ds_read_b64_tr_b16 v[234:235], v191 offset:0x2000
	ds_read_b64_tr_b16 v[236:237], v191 offset:0x2800
	ds_read_b64_tr_b16 v[238:239], v191 offset:0x3000
	ds_read_b64_tr_b16 v[240:241], v191 offset:0x3800
	s_waitcnt lgkmcnt(6)
	v_mfma_f32_32x32x16_bf16 v[48:63], v[146:149], v[72:75], v[48:63]
	ds_read_b64_tr_b16 v[72:73], v191 offset:0x200
	ds_read_b64_tr_b16 v[74:75], v191 offset:0xa00
	v_exp_f32_e32 v96, v96
	v_exp_f32_e32 v97, v97
	s_waitcnt lgkmcnt(6)
	v_mfma_f32_32x32x16_bf16 v[48:63], v[150:153], v[76:79], v[48:63]
	ds_read_b64_tr_b16 v[76:77], v191 offset:0x1200
	ds_read_b64_tr_b16 v[78:79], v191 offset:0x1a00
	v_exp_f32_e32 v98, v98
	v_exp_f32_e32 v99, v99

; #define SBAR() __builtin_amdgcn_sched_barrier(0)
; #define SLOAD(i, k0) do { sr_[i].vs0 = *reinterpret_cast<const bf16x8*>(&Vh[(size_t)((k0) + sr) * ldk + sc]); sr_[i].vs1 = *reinterpret_cast<const bf16x8*>(&Vh[(size_t)((k0) + 32 + sr) * ldk + sc]); \
;     sr_[i].ks0 = *reinterpret_cast<const bf16x8*>(&Kh[(size_t)((k0) + sr) * ldk + sc]); sr_[i].ks1 = *reinterpret_cast<const bf16x8*>(&Kh[(size_t)((k0) + 32 + sr) * ldk + sc]); } while (0)
; #define SWRITE(b, i) do { *(bf16x8*)((char*)V_lds + (b) * SHM_V + vst0) = sr_[i].vs0;          \
;     *(bf16x8*)((char*)V_lds + (b) * SHM_V + vst1) = sr_[i].vs1; int kc = sc * 2;               \
;     *(bf16x8*)((char*)K_lds + (b) * SHM_K + KSWZ(sr, kc)) = sr_[i].ks0;                       \
;     *(bf16x8*)((char*)K_lds + (b) * SHM_K + KSWZ(32 + sr, kc)) = sr_[i].ks1; } while (0)
; #define SWAIT() asm volatile("s_waitcnt vmcnt(4)" ::: "memory")
; template <int OFF> DEVINL s16x4 tr_read(int vb) {
;   s16x4 r; asm volatile("ds_read_b64_tr_b16 %0, %1 offset:%2" : "=&v"(r) : "v"(vb), "i"(OFF) : "memory"); return r;
; }
; template <int D0> DEVINL void pv_one(f32x16& od, int vb, bf16x8 pa0, bf16x8 pa1, bf16x8 pa2, bf16x8 pa3) {
;   const s16x4 l0 = tr_read<v_rd_off(D0, 0, 0)>(vb), h0 = tr_read<v_rd_off(D0, 0, 1)>(vb), l1 = tr_read<v_rd_off(D0, 1, 0)>(vb), h1 = tr_read<v_rd_off(D0, 1, 1)>(vb);
;   const s16x4 l2 = tr_read<v_rd_off(D0, 2, 0)>(vb), h2 = tr_read<v_rd_off(D0, 2, 1)>(vb), l3 = tr_read<v_rd_off(D0, 3, 0)>(vb), h3 = tr_read<v_rd_off(D0, 3, 1)>(vb);
;   asm volatile("s_waitcnt lgkmcnt(0)" ::: "memory"); SBAR();
;     ...
;   od = __builtin_amdgcn_mfma_f32_32x32x16_bf16(pa0, PK(l0, h0), od, 0, 0, 0);
;   od = __builtin_amdgcn_mfma_f32_32x32x16_bf16(pa1, PK(l1, h1), od, 0, 0, 0);
;   od = __builtin_amdgcn_mfma_f32_32x32x16_bf16(pa2, PK(l2, h2), od, 0, 0, 0);
;   od = __builtin_amdgcn_mfma_f32_32x32x16_bf16(pa3, PK(l3, h3), od, 0, 0, 0);
;     ...
; }
; DEVINL void pv_d0(f32x16* o, int vb, bf16x8 pa0, bf16x8 pa1, bf16x8 pa2, bf16x8 pa3) {
;   pv_one<0>(o[0], vb, pa0, pa1, pa2, pa3); pv_one<1>(o[1], vb, pa0, pa1, pa2, pa3); pv_one<2>(o[2], vb, pa0, pa1, pa2, pa3); pv_one<3>(o[3], vb, pa0, pa1, pa2, pa3);
; }
; template <bool DIFF, bool FAST> ...
;     ...
;     SLOAD(SO, (j + 2) * KVBLK); SBAR();
;     pv_d0(o, vb0, paA0, paA1, pa2, pa3); partialSM_bal(pB0, psB, paB0, paB1);
;     __syncthreads(); SWAIT(); SWRITE(0, SE);
	s_waitcnt lgkmcnt(6)
	v_mfma_f32_32x32x16_bf16 v[48:63], v[64:67], v[234:237], v[48:63]
	ds_read_b64_tr_b16 v[234:235], v191 offset:0x2200
	ds_read_b64_tr_b16 v[236:237], v191 offset:0x2a00
	v_exp_f32_e32 v100, v100
	v_exp_f32_e32 v101, v101
	s_waitcnt lgkmcnt(6)
	v_mfma_f32_32x32x16_bf16 v[48:63], v[68:71], v[238:241], v[48:63]
	ds_read_b64_tr_b16 v[238:239], v191 offset:0x3200
	ds_read_b64_tr_b16 v[240:241], v191 offset:0x3a00
	v_exp_f32_e32 v102, v102
	v_exp_f32_e32 v103, v103
	s_waitcnt lgkmcnt(6)
	v_mfma_f32_32x32x16_bf16 v[32:47], v[146:149], v[72:75], v[32:47]
	ds_read_b64_tr_b16 v[72:73], v191 offset:0x400
	ds_read_b64_tr_b16 v[74:75], v191 offset:0xc00
	v_exp_f32_e32 v104, v104
	v_exp_f32_e32 v105, v105
	s_waitcnt lgkmcnt(6)
	v_mfma_f32_32x32x16_bf16 v[32:47], v[150:153], v[76:79], v[32:47]
	ds_read_b64_tr_b16 v[76:77], v191 offset:0x1400
	ds_read_b64_tr_b16 v[78:79], v191 offset:0x1c00
	v_exp_f32_e32 v106, v106
	v_exp_f32_e32 v107, v107
	s_waitcnt lgkmcnt(6)
	v_mfma_f32_32x32x16_bf16 v[32:47], v[64:67], v[234:237], v[32:47]
	ds_read_b64_tr_b16 v[234:235], v191 offset:0x2400
	ds_read_b64_tr_b16 v[236:237], v191 offset:0x2c00
	v_exp_f32_e32 v108, v108
	v_exp_f32_e32 v109, v109
	v_add_f32_e32 v192, 0, v96
	v_add_f32_e32 v192, v97, v192
	s_waitcnt lgkmcnt(6)
	v_mfma_f32_32x32x16_bf16 v[32:47], v[68:71], v[238:241], v[32:47]
	ds_read_b64_tr_b16 v[238:239], v191 offset:0x3400
	ds_read_b64_tr_b16 v[240:241], v191 offset:0x3c00
	v_exp_f32_e32 v110, v110
	v_exp_f32_e32 v111, v111
	v_add_f32_e32 v192, v98, v192
	v_add_f32_e32 v192, v99, v192
	s_waitcnt lgkmcnt(6)
	v_mfma_f32_32x32x16_bf16 v[16:31], v[146:149], v[72:75], v[16:31]
	ds_read_b64_tr_b16 v[72:73], v191 offset:0x600
	ds_read_b64_tr_b16 v[74:75], v191 offset:0xe00
	v_add_f32_e32 v192, v100, v192
	v_add_f32_e32 v192, v101, v192
	s_waitcnt lgkmcnt(6)
	v_mfma_f32_32x32x16_bf16 v[16:31], v[150:153], v[76:79], v[16:31]
	ds_read_b64_tr_b16 v[76:77], v191 offset:0x1600
	ds_read_b64_tr_b16 v[78:79], v191 offset:0x1e00
	v_add_f32_e32 v192, v102, v192
	v_add_f32_e32 v192, v103, v192
	s_waitcnt lgkmcnt(6)
	v_mfma_f32_32x32x16_bf16 v[16:31], v[64:67], v[234:237], v[16:31]
	ds_read_b64_tr_b16 v[234:235], v191 offset:0x2600
	ds_read_b64_tr_b16 v[236:237], v191 offset:0x2e00
	v_add_f32_e32 v192, v104, v192
	v_add_f32_e32 v192, v105, v192
	s_waitcnt lgkmcnt(6)
	v_mfma_f32_32x32x16_bf16 v[16:31], v[68:71], v[238:241], v[16:31]
	ds_read_b64_tr_b16 v[238:239], v191 offset:0x3600
	ds_read_b64_tr_b16 v[240:241], v191 offset:0x3e00
	v_add_f32_e32 v192, v106, v192
	v_add_f32_e32 v192, v107, v192
	s_waitcnt lgkmcnt(6)
	v_mfma_f32_32x32x16_bf16 v[0:15], v[146:149], v[72:75], v[0:15]
	v_add_f32_e32 v192, v108, v192
	v_add_f32_e32 v192, v109, v192
	v_cvt_pk_bf16_f32 v146, v96, v97
	v_cvt_pk_bf16_f32 v147, v98, v99
	v_cvt_pk_bf16_f32 v148, v100, v101
	v_cvt_pk_bf16_f32 v149, v102, v103
	s_waitcnt lgkmcnt(4)
	v_mfma_f32_32x32x16_bf16 v[0:15], v[150:153], v[76:79], v[0:15]
	v_add_f32_e32 v192, v110, v192
	v_add_f32_e32 v192, v111, v192
	v_cvt_pk_bf16_f32 v150, v104, v105
	v_cvt_pk_bf16_f32 v151, v106, v107
	v_cvt_pk_bf16_f32 v152, v108, v109
	v_cvt_pk_bf16_f32 v153, v110, v111
	v_permlane32_swap_b32_e32 v146, v148
	v_permlane32_swap_b32_e32 v147, v149
	s_waitcnt lgkmcnt(2)
	v_mfma_f32_32x32x16_bf16 v[0:15], v[64:67], v[234:237], v[0:15]
	v_permlane32_swap_b32_e32 v150, v152
	v_permlane32_swap_b32_e32 v151, v153
	s_waitcnt lgkmcnt(0)
	v_mfma_f32_32x32x16_bf16 v[0:15], v[68:71], v[238:241], v[0:15]
	s_waitcnt vmcnt(0)
	s_waitcnt lgkmcnt(0)
	s_barrier
; #define SBAR() __builtin_amdgcn_sched_barrier(0)
; #define SLOAD(i, k0) do { sr_[i].vs0 = *reinterpret_cast<const bf16x8*>(&Vh[(size_t)((k0) + sr) * ldk + sc]); sr_[i].vs1 = *reinterpret_cast<const bf16x8*>(&Vh[(size_t)((k0) + 32 + sr) * ldk + sc]); \
;     sr_[i].ks0 = *reinterpret_cast<const bf16x8*>(&Kh[(size_t)((k0) + sr) * ldk + sc]); sr_[i].ks1 = *reinterpret_cast<const bf16x8*>(&Kh[(size_t)((k0) + 32 + sr) * ldk + sc]); } while (0)
; DEVINL void partialSM_bal(f32x16& p0, float& ps, bf16x8& pa0, bf16x8& pa1) {
; #pragma unroll
;   for (int r = 0; r < 16; ++r) p0[r] = __builtin_amdgcn_exp2f(p0[r]);
;   float s = 0;
; #pragma unroll
;   for (int r = 0; r < 16; ++r) s += p0[r];
;   ps = s;
;   PK4F(p0, 0, pa0); PK4F(p0, 8, pa1);
; }
; DEVINL void finishSM_bal(f32x16& p1, float ps, float& l_reg, bf16x8& pa2, bf16x8& pa3) {
; #pragma unroll
;   for (int r = 0; r < 16; ++r) p1[r] = __builtin_amdgcn_exp2f(p1[r]);
; #pragma unroll
;   for (int r = 0; r < 16; ++r) ps += p1[r];
;   { auto rr = __builtin_amdgcn_permlane32_swap(__float_as_uint(ps), __float_as_uint(ps), false, false);
;     ps = __uint_as_float(rr[0]) + __uint_as_float(rr[1]); }
;   l_reg += ps;
;   PK4F(p1, 0, pa2); PK4F(p1, 8, pa3);
; }
; template <int ND0>
; DEVINL void qkt(f32x16& p0, f32x16& p1, const bf16* Ks, const bf16x8* qr, int r32, int hi, int colbase) {
;   p0 = f32x16{}; p1 = f32x16{};
;   __builtin_amdgcn_iglp_opt(1);
; #pragma unroll
;   for (int d0 = 0; d0 < ND0; ++d0) { int cb = (colbase + d0 * 16 + hi * 8) * 2;
;     bf16x8 b0 = *reinterpret_cast<const bf16x8*>((const char*)Ks + KSWZ(r32, cb));
;     bf16x8 b1 = *reinterpret_cast<const bf16x8*>((const char*)Ks + KSWZ(32 + r32, cb));
;     p0 = __builtin_amdgcn_mfma_f32_32x32x16_bf16(b0, qr[d0], p0, 0, 0, 0);
;     p1 = __builtin_amdgcn_mfma_f32_32x32x16_bf16(b1, qr[d0], p1, 0, 0, 0); }
; }
; template <bool DIFF, bool FAST> ...
;     ...
;     __syncthreads();
;     SBAR(); qkt<ND0>(pA0, pA1, K_lds, qr, r32, hi, colbase);
;     finishSM_bal(pB1, psB, l_reg, pa2, pa3); SBAR();
;     SLOAD(SE, (j + 3 < NT ? j + 3 : NT - 1) * KVBLK);     SBAR();
;     pv_d0(o, vb0 + (int)SHM_V, paB0, paB1, pa2, pa3); partialSM_bal(pA0, psA, paA0, paA1);
	ds_read_b128 v[64:67], v224 offset:32768
	ds_read_b128 v[68:71], v224 offset:40960
	ds_read_b128 v[154:157], v225 offset:32768
	ds_read_b128 v[158:161], v225 offset:40960
	ds_read_b128 v[162:165], v226 offset:32768
	ds_read_b128 v[234:237], v226 offset:40960
	ds_read_b128 v[238:241], v227 offset:32768
	ds_read_b128 v[242:245], v227 offset:40960
	s_add_i32 s9, s7, -1
	s_lshl_b32 s9, s9, 15
	s_add_u32 s26, s10, s9
	s_addc_u32 s27, s11, 0
	s_add_u32 m0, vcc_lo, vcc_hi
	s_add_u32 m0, m0, 0x4000
	s_nop 0
	global_load_lds_dwordx4 v218, s[26:27]
	v_exp_f32_e32 v80, v80
	v_exp_f32_e32 v83, v83
	s_waitcnt lgkmcnt(7)
	v_mfma_f32_32x32x16_bf16 v[96:111], v[64:67], v[142:145], 0
	s_add_u32 s26, s26, 0x4000
	s_addc_u32 s27, s27, 0
	s_add_u32 m0, m0, 0x2000
	s_nop 0
	global_load_lds_dwordx4 v218, s[26:27]
	v_exp_f32_e32 v84, v84
	v_exp_f32_e32 v85, v85
	s_waitcnt lgkmcnt(6)
	v_mfma_f32_32x32x16_bf16 v[64:79], v[68:71], v[142:145], 0
	s_add_u32 s26, s28, s9
	s_addc_u32 s27, s29, 0
	s_add_u32 m0, vcc_lo, 0xc000
	s_nop 0
	global_load_lds_dwordx4 v233, s[26:27]
	v_exp_f32_e32 v86, v86
	v_exp_f32_e32 v87, v87
	s_waitcnt lgkmcnt(5)
	v_mfma_f32_32x32x16_bf16 v[96:111], v[154:157], v[138:141], v[96:111]
	ds_read_b128 v[154:157], v228 offset:32768
	s_add_u32 s26, s26, 0x4000
	s_addc_u32 s27, s27, 0
	s_add_u32 m0, m0, 0x2000
	s_nop 0
	global_load_lds_dwordx4 v233, s[26:27]
	v_exp_f32_e32 v88, v88
	v_exp_f32_e32 v89, v89
	s_waitcnt lgkmcnt(5)
	v_mfma_f32_32x32x16_bf16 v[64:79], v[158:161], v[138:141], v[64:79]
	ds_read_b128 v[158:161], v228 offset:40960
	v_exp_f32_e32 v90, v90
	v_exp_f32_e32 v91, v91
	s_waitcnt lgkmcnt(5)
	v_mfma_f32_32x32x16_bf16 v[96:111], v[162:165], v[134:137], v[96:111]
	ds_read_b128 v[162:165], v229 offset:32768
	v_exp_f32_e32 v92, v92
	v_exp_f32_e32 v93, v93
	s_waitcnt lgkmcnt(5)
	v_mfma_f32_32x32x16_bf16 v[64:79], v[234:237], v[134:137], v[64:79]
	ds_read_b128 v[234:237], v229 offset:40960
	v_exp_f32_e32 v94, v94
	v_exp_f32_e32 v95, v95
	s_waitcnt lgkmcnt(5)
	v_mfma_f32_32x32x16_bf16 v[96:111], v[238:241], v[130:133], v[96:111]
	ds_read_b128 v[238:241], v231 offset:32768
	v_exp_f32_e32 v166, v81
	v_exp_f32_e32 v167, v82
	s_waitcnt lgkmcnt(5)
	v_mfma_f32_32x32x16_bf16 v[64:79], v[242:245], v[130:133], v[64:79]
	ds_read_b128 v[242:245], v231 offset:40960
	v_add_f32_e32 v81, v80, v192
	v_add_f32_e32 v81, v166, v81
	v_add_f32_e32 v81, v167, v81
	v_add_f32_e32 v81, v83, v81
	s_waitcnt lgkmcnt(5)
	v_mfma_f32_32x32x16_bf16 v[96:111], v[154:157], v[126:129], v[96:111]
	ds_read_b128 v[154:157], v230 offset:32768
	v_add_f32_e32 v81, v84, v81
	v_add_f32_e32 v81, v85, v81
	v_add_f32_e32 v81, v86, v81
	v_add_f32_e32 v81, v87, v81
	s_waitcnt lgkmcnt(5)
	v_mfma_f32_32x32x16_bf16 v[64:79], v[158:161], v[126:129], v[64:79]
	ds_read_b128 v[158:161], v230 offset:40960
	v_add_f32_e32 v81, v88, v81
	v_add_f32_e32 v81, v89, v81
	v_add_f32_e32 v81, v90, v81
	v_add_f32_e32 v81, v91, v81
	s_waitcnt lgkmcnt(5)
	v_mfma_f32_32x32x16_bf16 v[96:111], v[162:165], v[122:125], v[96:111]
	v_add_f32_e32 v81, v92, v81
	v_add_f32_e32 v81, v93, v81
	v_add_f32_e32 v81, v94, v81
	v_add_f32_e32 v81, v95, v81
	s_waitcnt lgkmcnt(4)
	v_mfma_f32_32x32x16_bf16 v[64:79], v[234:237], v[122:125], v[64:79]
	v_mov_b32_e32 v82, v81
	s_nop 1
	v_permlane32_swap_b32_e32 v81, v82
	v_add_f32_e32 v81, v81, v82
	s_waitcnt lgkmcnt(3)
	v_mfma_f32_32x32x16_bf16 v[96:111], v[238:241], v[118:121], v[96:111]
	v_cvt_pk_bf16_f32 v82, v80, v166
	v_cvt_pk_bf16_f32 v83, v167, v83
	v_cvt_pk_bf16_f32 v84, v84, v85
	v_cvt_pk_bf16_f32 v85, v86, v87
	s_waitcnt lgkmcnt(2)
	v_mfma_f32_32x32x16_bf16 v[64:79], v[242:245], v[118:121], v[64:79]
	v_cvt_pk_bf16_f32 v86, v88, v89
	v_cvt_pk_bf16_f32 v87, v90, v91
	v_cvt_pk_bf16_f32 v88, v92, v93
	v_cvt_pk_bf16_f32 v89, v94, v95
	s_waitcnt lgkmcnt(1)
	v_mfma_f32_32x32x16_bf16 v[96:111], v[154:157], v[114:117], v[96:111]
	v_permlane32_swap_b32_e32 v82, v84
	v_permlane32_swap_b32_e32 v83, v85
	v_permlane32_swap_b32_e32 v86, v88
	v_permlane32_swap_b32_e32 v87, v89
	s_waitcnt lgkmcnt(0)
	v_mfma_f32_32x32x16_bf16 v[64:79], v[158:161], v[114:117], v[64:79]
	ds_read_b64_tr_b16 v[90:91], v222 offset:0
	ds_read_b64_tr_b16 v[92:93], v222 offset:0x800
	ds_read_b64_tr_b16 v[234:235], v222 offset:0x1000
	ds_read_b64_tr_b16 v[236:237], v222 offset:0x1800
	ds_read_b64_tr_b16 v[238:239], v222 offset:0x2000
	ds_read_b64_tr_b16 v[240:241], v222 offset:0x2800
	ds_read_b64_tr_b16 v[242:243], v222 offset:0x3000
	ds_read_b64_tr_b16 v[244:245], v222 offset:0x3800
	s_waitcnt lgkmcnt(6)
	v_mfma_f32_32x32x16_bf16 v[48:63], v[146:149], v[90:93], v[48:63]
	ds_read_b64_tr_b16 v[90:91], v222 offset:0x200
	ds_read_b64_tr_b16 v[92:93], v222 offset:0xa00
	v_exp_f32_e32 v96, v96
	v_exp_f32_e32 v97, v97
	s_waitcnt lgkmcnt(6)
	v_mfma_f32_32x32x16_bf16 v[48:63], v[150:153], v[234:237], v[48:63]
	ds_read_b64_tr_b16 v[234:235], v222 offset:0x1200
	ds_read_b64_tr_b16 v[236:237], v222 offset:0x1a00
	v_exp_f32_e32 v98, v98
	v_exp_f32_e32 v99, v99

; #define SBAR() __builtin_amdgcn_sched_barrier(0)
; #define SLOAD(i, k0) do { sr_[i].vs0 = *reinterpret_cast<const bf16x8*>(&Vh[(size_t)((k0) + sr) * ldk + sc]); sr_[i].vs1 = *reinterpret_cast<const bf16x8*>(&Vh[(size_t)((k0) + 32 + sr) * ldk + sc]); \
;     sr_[i].ks0 = *reinterpret_cast<const bf16x8*>(&Kh[(size_t)((k0) + sr) * ldk + sc]); sr_[i].ks1 = *reinterpret_cast<const bf16x8*>(&Kh[(size_t)((k0) + 32 + sr) * ldk + sc]); } while (0)
; #define SWRITE(b, i) do { *(bf16x8*)((char*)V_lds + (b) * SHM_V + vst0) = sr_[i].vs0;          \
;     *(bf16x8*)((char*)V_lds + (b) * SHM_V + vst1) = sr_[i].vs1; int kc = sc * 2;               \
;     *(bf16x8*)((char*)K_lds + (b) * SHM_K + KSWZ(sr, kc)) = sr_[i].ks0;                       \
;     *(bf16x8*)((char*)K_lds + (b) * SHM_K + KSWZ(32 + sr, kc)) = sr_[i].ks1; } while (0)
; template <int OFF> DEVINL s16x4 tr_read(int vb) {
;   s16x4 r; asm volatile("ds_read_b64_tr_b16 %0, %1 offset:%2" : "=&v"(r) : "v"(vb), "i"(OFF) : "memory"); return r;
; }
; template <int D0> DEVINL void pv_one(f32x16& od, int vb, bf16x8 pa0, bf16x8 pa1, bf16x8 pa2, bf16x8 pa3) {
;   const s16x4 l0 = tr_read<v_rd_off(D0, 0, 0)>(vb), h0 = tr_read<v_rd_off(D0, 0, 1)>(vb), l1 = tr_read<v_rd_off(D0, 1, 0)>(vb), h1 = tr_read<v_rd_off(D0, 1, 1)>(vb);
;   const s16x4 l2 = tr_read<v_rd_off(D0, 2, 0)>(vb), h2 = tr_read<v_rd_off(D0, 2, 1)>(vb), l3 = tr_read<v_rd_off(D0, 3, 0)>(vb), h3 = tr_read<v_rd_off(D0, 3, 1)>(vb);
;   asm volatile("s_waitcnt lgkmcnt(0)" ::: "memory"); SBAR();
;     ...
;   od = __builtin_amdgcn_mfma_f32_32x32x16_bf16(pa0, PK(l0, h0), od, 0, 0, 0);
;   od = __builtin_amdgcn_mfma_f32_32x32x16_bf16(pa1, PK(l1, h1), od, 0, 0, 0);
;   od = __builtin_amdgcn_mfma_f32_32x32x16_bf16(pa2, PK(l2, h2), od, 0, 0, 0);
;   od = __builtin_amdgcn_mfma_f32_32x32x16_bf16(pa3, PK(l3, h3), od, 0, 0, 0);
;     ...
; }
; DEVINL void pv_d0(f32x16* o, int vb, bf16x8 pa0, bf16x8 pa1, bf16x8 pa2, bf16x8 pa3) {
;   pv_one<0>(o[0], vb, pa0, pa1, pa2, pa3); pv_one<1>(o[1], vb, pa0, pa1, pa2, pa3); pv_one<2>(o[2], vb, pa0, pa1, pa2, pa3); pv_one<3>(o[3], vb, pa0, pa1, pa2, pa3);
; }
; template <bool DIFF, bool FAST> ...
;     ...
;     SLOAD(SE, (j + 3 < NT ? j + 3 : NT - 1) * KVBLK);     SBAR();
;     pv_d0(o, vb0 + (int)SHM_V, paB0, paB1, pa2, pa3); partialSM_bal(pA0, psA, paA0, paA1);
;     __syncthreads(); SWAIT(); SWRITE(1, SO);
;     __syncthreads();
	s_waitcnt lgkmcnt(6)
	v_mfma_f32_32x32x16_bf16 v[48:63], v[82:85], v[238:241], v[48:63]
	ds_read_b64_tr_b16 v[238:239], v222 offset:0x2200
	ds_read_b64_tr_b16 v[240:241], v222 offset:0x2a00
	v_exp_f32_e32 v100, v100
	v_exp_f32_e32 v101, v101
	s_waitcnt lgkmcnt(6)
	v_mfma_f32_32x32x16_bf16 v[48:63], v[86:89], v[242:245], v[48:63]
	ds_read_b64_tr_b16 v[242:243], v222 offset:0x3200
	ds_read_b64_tr_b16 v[244:245], v222 offset:0x3a00
	v_exp_f32_e32 v102, v102
	v_exp_f32_e32 v103, v103
	s_waitcnt lgkmcnt(6)
	v_mfma_f32_32x32x16_bf16 v[32:47], v[146:149], v[90:93], v[32:47]
	ds_read_b64_tr_b16 v[90:91], v222 offset:0x400
	ds_read_b64_tr_b16 v[92:93], v222 offset:0xc00
	v_exp_f32_e32 v104, v104
	v_exp_f32_e32 v105, v105
	s_waitcnt lgkmcnt(6)
	v_mfma_f32_32x32x16_bf16 v[32:47], v[150:153], v[234:237], v[32:47]
	ds_read_b64_tr_b16 v[234:235], v222 offset:0x1400
	ds_read_b64_tr_b16 v[236:237], v222 offset:0x1c00
	v_exp_f32_e32 v106, v106
	v_exp_f32_e32 v107, v107
	s_waitcnt lgkmcnt(6)
	v_mfma_f32_32x32x16_bf16 v[32:47], v[82:85], v[238:241], v[32:47]
	ds_read_b64_tr_b16 v[238:239], v222 offset:0x2400
	ds_read_b64_tr_b16 v[240:241], v222 offset:0x2c00
	v_exp_f32_e32 v108, v108
	v_exp_f32_e32 v196, v109
	v_add_f32_e32 v194, 0, v96
	v_add_f32_e32 v194, v97, v194
	s_waitcnt lgkmcnt(6)
	v_mfma_f32_32x32x16_bf16 v[32:47], v[86:89], v[242:245], v[32:47]
	ds_read_b64_tr_b16 v[242:243], v222 offset:0x3400
	ds_read_b64_tr_b16 v[244:245], v222 offset:0x3c00
	v_exp_f32_e32 v192, v110
	v_exp_f32_e32 v80, v111
	v_add_f32_e32 v194, v98, v194
	v_add_f32_e32 v194, v99, v194
	s_waitcnt lgkmcnt(6)
	v_mfma_f32_32x32x16_bf16 v[16:31], v[146:149], v[90:93], v[16:31]
	ds_read_b64_tr_b16 v[90:91], v222 offset:0x600
	ds_read_b64_tr_b16 v[92:93], v222 offset:0xe00
	v_add_f32_e32 v194, v100, v194
	v_add_f32_e32 v194, v101, v194
	s_waitcnt lgkmcnt(6)
	v_mfma_f32_32x32x16_bf16 v[16:31], v[150:153], v[234:237], v[16:31]
	ds_read_b64_tr_b16 v[234:235], v222 offset:0x1600
	ds_read_b64_tr_b16 v[236:237], v222 offset:0x1e00
	v_add_f32_e32 v194, v102, v194
	v_add_f32_e32 v194, v103, v194
	s_waitcnt lgkmcnt(6)
	v_mfma_f32_32x32x16_bf16 v[16:31], v[82:85], v[238:241], v[16:31]
	ds_read_b64_tr_b16 v[238:239], v222 offset:0x2600
	ds_read_b64_tr_b16 v[240:241], v222 offset:0x2e00
	v_add_f32_e32 v194, v104, v194
	v_add_f32_e32 v194, v105, v194
	s_waitcnt lgkmcnt(6)
	v_mfma_f32_32x32x16_bf16 v[16:31], v[86:89], v[242:245], v[16:31]
	ds_read_b64_tr_b16 v[242:243], v222 offset:0x3600
	ds_read_b64_tr_b16 v[244:245], v222 offset:0x3e00
	v_add_f32_e32 v194, v106, v194
	v_add_f32_e32 v194, v107, v194
	s_waitcnt lgkmcnt(6)
	v_mfma_f32_32x32x16_bf16 v[0:15], v[146:149], v[90:93], v[0:15]
	v_add_f32_e32 v194, v108, v194
	v_cvt_pk_bf16_f32 v146, v96, v97
	v_cvt_pk_bf16_f32 v147, v98, v99
	v_cvt_pk_bf16_f32 v148, v100, v101
	v_cvt_pk_bf16_f32 v149, v102, v103
	s_waitcnt lgkmcnt(4)
	v_mfma_f32_32x32x16_bf16 v[0:15], v[150:153], v[234:237], v[0:15]
	v_cvt_pk_bf16_f32 v150, v104, v105
	v_cvt_pk_bf16_f32 v151, v106, v107
	v_cvt_pk_bf16_f32 v152, v108, v196
	v_cvt_pk_bf16_f32 v153, v192, v80
	v_permlane32_swap_b32_e32 v146, v148
	v_permlane32_swap_b32_e32 v147, v149
	s_waitcnt lgkmcnt(2)
	v_mfma_f32_32x32x16_bf16 v[0:15], v[82:85], v[238:241], v[0:15]
	v_permlane32_swap_b32_e32 v150, v152
	v_permlane32_swap_b32_e32 v151, v153
	v_pk_add_f32 v[82:83], v[196:197], v[194:195]
	v_pk_add_f32 v[82:83], v[192:193], v[82:83]
	v_pk_add_f32 v[194:195], v[80:81], v[82:83]
	v_xor_b32_e32 v191, 0x10000, v191
	v_xor_b32_e32 v222, 0x10000, v222
	s_xor_b32 vcc_hi, vcc_hi, 0x10000
	s_waitcnt lgkmcnt(0)
	v_mfma_f32_32x32x16_bf16 v[0:15], v[86:89], v[242:245], v[0:15]
	s_add_i32 s9, s7, 2
	s_add_i32 s7, s7, -1
	v_mov_b32_e32 v193, v195
	s_cmp_ge_i32 s7, s6
	s_mov_b32 s7, s9
	s_waitcnt vmcnt(0)
	s_waitcnt lgkmcnt(0)
	s_barrier
	s_cbranch_scc0 .Lattn_gqa_top
	s_branch .LBB0_566

; #define SBAR() __builtin_amdgcn_sched_barrier(0)
; #define SLOAD(i, k0) do { sr_[i].vs0 = *reinterpret_cast<const bf16x8*>(&Vh[(size_t)((k0) + sr) * ldk + sc]); sr_[i].vs1 = *reinterpret_cast<const bf16x8*>(&Vh[(size_t)((k0) + 32 + sr) * ldk + sc]); \
;     sr_[i].ks0 = *reinterpret_cast<const bf16x8*>(&Kh[(size_t)((k0) + sr) * ldk + sc]); sr_[i].ks1 = *reinterpret_cast<const bf16x8*>(&Kh[(size_t)((k0) + 32 + sr) * ldk + sc]); } while (0)
; #define SWRITE(b, i) do { *(bf16x8*)((char*)V_lds + (b) * SHM_V + vst0) = sr_[i].vs0;          \
;     *(bf16x8*)((char*)V_lds + (b) * SHM_V + vst1) = sr_[i].vs1; int kc = sc * 2;               \
;     *(bf16x8*)((char*)K_lds + (b) * SHM_K + KSWZ(sr, kc)) = sr_[i].ks0;                       \
;     *(bf16x8*)((char*)K_lds + (b) * SHM_K + KSWZ(32 + sr, kc)) = sr_[i].ks1; } while (0)
; #define SWAIT() asm volatile("s_waitcnt vmcnt(4)" ::: "memory")
; template <bool DIFF, bool FAST> ...
;     ...
;   for (int j = 1; j + 1 < NT; j += 2) {
;     SBAR(); qkt<ND0>(pB0, pB1, (bf16*)((char*)K_lds + SHM_K), qr, r32, hi, colbase);
;     finishSM_bal(pA1, psA, l_reg, pa2, pa3); SBAR();
;     SLOAD(SO, (j + 2) * KVBLK); SBAR();
;     pv_d0(o, vb0, paA0, paA1, pa2, pa3); partialSM_bal(pB0, psB, paB0, paB1);
;     __syncthreads(); SWAIT(); SWRITE(0, SE);
.LBB0_607:
	v_readfirstlane_b32 vcc_lo, v182
	s_lshr_b32 vcc_lo, vcc_lo, 6
	s_lshl_b32 vcc_lo, vcc_lo, 10
	s_mov_b32 vcc_hi, 0x10000
	v_lshrrev_b32_e32 v213, 4, v182
	v_and_b32_e32 v190, 15, v213
	v_xor_b32_e32 v190, v190, v182
	v_and_b32_e32 v190, 15, v190
	v_lshlrev_b32_e32 v213, 11, v213
	v_lshl_add_u32 v213, v190, 4, v213
	v_bfe_u32 v184, v182, 2, 2
	v_bfe_u32 v190, v182, 7, 1
	v_lshl_or_b32 v184, v190, 2, v184
	v_bfe_u32 v190, v182, 4, 1
	v_lshl_or_b32 v184, v190, 3, v184
	v_bfe_u32 v190, v182, 8, 1
	v_lshl_or_b32 v184, v190, 4, v184
	v_lshlrev_b32_e32 v184, 11, v184
	v_and_b32_e32 v190, 3, v182
	v_lshl_or_b32 v184, v190, 4, v184
	v_bfe_u32 v190, v182, 5, 2
	v_lshl_or_b32 v184, v190, 6, v184
	s_waitcnt vmcnt(0)
.Lattn_diff_top:
	ds_read_b128 v[80:83], v194 offset:49152
	ds_read_b128 v[84:87], v194 offset:57344
	ds_read_b128 v[154:157], v197 offset:49152
	ds_read_b128 v[158:161], v197 offset:57344
	ds_read_b128 v[162:165], v196 offset:49152
	ds_read_b128 v[166:169], v196 offset:57344
	ds_read_b128 v[214:217], v195 offset:49152
	ds_read_b128 v[218:221], v195 offset:57344
	s_add_i32 s9, s7, -2
	s_lshl_b32 s9, s9, 17
	s_add_u32 s10, s18, s9
	s_addc_u32 s11, s19, 0
	s_add_u32 m0, vcc_lo, vcc_hi
	s_nop 0
	global_load_lds_dwordx4 v184, s[10:11]
	v_exp_f32_e32 v64, v64
	v_exp_f32_e32 v65, v65
	v_exp_f32_e32 v66, v66
	s_waitcnt lgkmcnt(7)
	v_mfma_f32_32x32x16_bf16 v[96:111], v[80:83], v[126:129], 0
	s_add_u32 s10, s10, 0x10000
	s_addc_u32 s11, s11, 0
	s_add_u32 m0, m0, 0x2000
	s_nop 0
	global_load_lds_dwordx4 v184, s[10:11]
	v_exp_f32_e32 v67, v67
	v_exp_f32_e32 v68, v68
	v_exp_f32_e32 v69, v69
	s_waitcnt lgkmcnt(6)
	v_mfma_f32_32x32x16_bf16 v[80:95], v[84:87], v[126:129], 0
	s_add_u32 s10, s16, s9
	s_addc_u32 s11, s17, 0
	s_add_u32 m0, vcc_lo, 0x8000
	s_nop 0
	global_load_lds_dwordx4 v213, s[10:11]
	v_exp_f32_e32 v70, v70
	v_exp_f32_e32 v71, v71
	v_exp_f32_e32 v72, v72
	s_waitcnt lgkmcnt(5)
	v_mfma_f32_32x32x16_bf16 v[96:111], v[154:157], v[122:125], v[96:111]
	s_add_u32 s10, s10, 0x10000
	s_addc_u32 s11, s11, 0
	s_add_u32 m0, m0, 0x2000
	s_nop 0
	global_load_lds_dwordx4 v213, s[10:11]
	v_exp_f32_e32 v73, v73
	v_exp_f32_e32 v74, v74
	v_exp_f32_e32 v75, v75
	s_waitcnt lgkmcnt(4)
	v_mfma_f32_32x32x16_bf16 v[80:95], v[158:161], v[122:125], v[80:95]
	v_exp_f32_e32 v76, v76
	v_exp_f32_e32 v77, v77
	v_exp_f32_e32 v78, v78
	s_waitcnt lgkmcnt(3)
	v_mfma_f32_32x32x16_bf16 v[96:111], v[162:165], v[118:121], v[96:111]
	v_exp_f32_e32 v79, v79
	v_add_f32_e32 v177, v174, v64
	v_add_f32_e32 v177, v65, v177
	v_add_f32_e32 v177, v66, v177
	v_add_f32_e32 v177, v67, v177
	v_add_f32_e32 v177, v68, v177
	s_waitcnt lgkmcnt(2)
	v_mfma_f32_32x32x16_bf16 v[80:95], v[166:169], v[118:121], v[80:95]
	v_add_f32_e32 v177, v69, v177
	v_add_f32_e32 v177, v70, v177
	v_add_f32_e32 v177, v71, v177
	v_add_f32_e32 v177, v72, v177
	v_add_f32_e32 v177, v73, v177
	v_add_f32_e32 v177, v74, v177
	v_add_f32_e32 v177, v75, v177
	s_waitcnt lgkmcnt(1)
	v_mfma_f32_32x32x16_bf16 v[96:111], v[214:217], v[114:117], v[96:111]
	v_add_f32_e32 v177, v76, v177
	v_add_f32_e32 v177, v77, v177
	v_add_f32_e32 v177, v78, v177
	v_add_f32_e32 v177, v79, v177
	v_cvt_pk_bf16_f32 v64, v64, v65
	v_cvt_pk_bf16_f32 v65, v66, v67
	v_cvt_pk_bf16_f32 v66, v68, v69
	s_waitcnt lgkmcnt(0)
	v_mfma_f32_32x32x16_bf16 v[80:95], v[218:221], v[114:117], v[80:95]
	v_cvt_pk_bf16_f32 v67, v70, v71
	v_cvt_pk_bf16_f32 v68, v72, v73
	v_cvt_pk_bf16_f32 v69, v74, v75
	v_cvt_pk_bf16_f32 v70, v76, v77
	v_cvt_pk_bf16_f32 v71, v78, v79
	v_mov_b32_e32 v175, v177
	v_permlane32_swap_b32_e32 v64, v66
	v_permlane32_swap_b32_e32 v65, v67
	v_permlane32_swap_b32_e32 v68, v70
	v_permlane32_swap_b32_e32 v69, v71
	v_permlane32_swap_b32_e32 v177, v175
	ds_read_b64_tr_b16 v[72:73], v171 offset:0
	ds_read_b64_tr_b16 v[74:75], v171 offset:0x800
	ds_read_b64_tr_b16 v[76:77], v171 offset:0x1000
	ds_read_b64_tr_b16 v[78:79], v171 offset:0x1800
	ds_read_b64_tr_b16 v[214:215], v171 offset:0x2000
	ds_read_b64_tr_b16 v[216:217], v171 offset:0x2800
	ds_read_b64_tr_b16 v[218:219], v171 offset:0x3000
	ds_read_b64_tr_b16 v[220:221], v171 offset:0x3800
	s_waitcnt lgkmcnt(6)
	v_mfma_f32_32x32x16_bf16 v[48:63], v[130:133], v[72:75], v[48:63]
	ds_read_b64_tr_b16 v[72:73], v171 offset:0x200
	ds_read_b64_tr_b16 v[74:75], v171 offset:0xa00
	v_exp_f32_e32 v96, v96
	v_exp_f32_e32 v97, v97
	s_waitcnt lgkmcnt(6)
	v_mfma_f32_32x32x16_bf16 v[48:63], v[134:137], v[76:79], v[48:63]
	ds_read_b64_tr_b16 v[76:77], v171 offset:0x1200
	ds_read_b64_tr_b16 v[78:79], v171 offset:0x1a00
	v_exp_f32_e32 v98, v98
	v_exp_f32_e32 v99, v99

; #define SBAR() __builtin_amdgcn_sched_barrier(0)
; #define SLOAD(i, k0) do { sr_[i].vs0 = *reinterpret_cast<const bf16x8*>(&Vh[(size_t)((k0) + sr) * ldk + sc]); sr_[i].vs1 = *reinterpret_cast<const bf16x8*>(&Vh[(size_t)((k0) + 32 + sr) * ldk + sc]); \
;     sr_[i].ks0 = *reinterpret_cast<const bf16x8*>(&Kh[(size_t)((k0) + sr) * ldk + sc]); sr_[i].ks1 = *reinterpret_cast<const bf16x8*>(&Kh[(size_t)((k0) + 32 + sr) * ldk + sc]); } while (0)
; #define SWRITE(b, i) do { *(bf16x8*)((char*)V_lds + (b) * SHM_V + vst0) = sr_[i].vs0;          \
;     *(bf16x8*)((char*)V_lds + (b) * SHM_V + vst1) = sr_[i].vs1; int kc = sc * 2;               \
;     *(bf16x8*)((char*)K_lds + (b) * SHM_K + KSWZ(sr, kc)) = sr_[i].ks0;                       \
;     *(bf16x8*)((char*)K_lds + (b) * SHM_K + KSWZ(32 + sr, kc)) = sr_[i].ks1; } while (0)
; #define SWAIT() asm volatile("s_waitcnt vmcnt(4)" ::: "memory")
; template <int OFF> DEVINL s16x4 tr_read(int vb) {
;   s16x4 r; asm volatile("ds_read_b64_tr_b16 %0, %1 offset:%2" : "=&v"(r) : "v"(vb), "i"(OFF) : "memory"); return r;
; }
; template <int D0> DEVINL void pv_one(f32x16& od, int vb, bf16x8 pa0, bf16x8 pa1, bf16x8 pa2, bf16x8 pa3) {
;   const s16x4 l0 = tr_read<v_rd_off(D0, 0, 0)>(vb), h0 = tr_read<v_rd_off(D0, 0, 1)>(vb), l1 = tr_read<v_rd_off(D0, 1, 0)>(vb), h1 = tr_read<v_rd_off(D0, 1, 1)>(vb);
;   const s16x4 l2 = tr_read<v_rd_off(D0, 2, 0)>(vb), h2 = tr_read<v_rd_off(D0, 2, 1)>(vb), l3 = tr_read<v_rd_off(D0, 3, 0)>(vb), h3 = tr_read<v_rd_off(D0, 3, 1)>(vb);
;   asm volatile("s_waitcnt lgkmcnt(0)" ::: "memory"); SBAR();
;     ...
;   od = __builtin_amdgcn_mfma_f32_32x32x16_bf16(pa0, PK(l0, h0), od, 0, 0, 0);
;   od = __builtin_amdgcn_mfma_f32_32x32x16_bf16(pa1, PK(l1, h1), od, 0, 0, 0);
;   od = __builtin_amdgcn_mfma_f32_32x32x16_bf16(pa2, PK(l2, h2), od, 0, 0, 0);
;   od = __builtin_amdgcn_mfma_f32_32x32x16_bf16(pa3, PK(l3, h3), od, 0, 0, 0);
;     ...
; }
; DEVINL void pv_d0(f32x16* o, int vb, bf16x8 pa0, bf16x8 pa1, bf16x8 pa2, bf16x8 pa3) {
;   pv_one<0>(o[0], vb, pa0, pa1, pa2, pa3); pv_one<1>(o[1], vb, pa0, pa1, pa2, pa3); pv_one<2>(o[2], vb, pa0, pa1, pa2, pa3); pv_one<3>(o[3], vb, pa0, pa1, pa2, pa3);
; }
; template <bool DIFF, bool FAST> ...
;     ...
;     SLOAD(SO, (j + 2) * KVBLK); SBAR();
;     pv_d0(o, vb0, paA0, paA1, pa2, pa3); partialSM_bal(pB0, psB, paB0, paB1);
;     __syncthreads(); SWAIT(); SWRITE(0, SE);
	s_waitcnt lgkmcnt(6)
	v_mfma_f32_32x32x16_bf16 v[48:63], v[64:67], v[214:217], v[48:63]
	ds_read_b64_tr_b16 v[214:215], v171 offset:0x2200
	ds_read_b64_tr_b16 v[216:217], v171 offset:0x2a00
	v_exp_f32_e32 v100, v100
	v_exp_f32_e32 v101, v101
	s_waitcnt lgkmcnt(6)
	v_mfma_f32_32x32x16_bf16 v[48:63], v[68:71], v[218:221], v[48:63]
	ds_read_b64_tr_b16 v[218:219], v171 offset:0x3200
	ds_read_b64_tr_b16 v[220:221], v171 offset:0x3a00
	v_exp_f32_e32 v102, v102
	v_exp_f32_e32 v103, v103
	s_waitcnt lgkmcnt(6)
	v_mfma_f32_32x32x16_bf16 v[32:47], v[130:133], v[72:75], v[32:47]
	ds_read_b64_tr_b16 v[72:73], v171 offset:0x400
	ds_read_b64_tr_b16 v[74:75], v171 offset:0xc00
	v_exp_f32_e32 v104, v104
	v_exp_f32_e32 v105, v105
	s_waitcnt lgkmcnt(6)
	v_mfma_f32_32x32x16_bf16 v[32:47], v[134:137], v[76:79], v[32:47]
	ds_read_b64_tr_b16 v[76:77], v171 offset:0x1400
	ds_read_b64_tr_b16 v[78:79], v171 offset:0x1c00
	v_exp_f32_e32 v106, v106
	v_exp_f32_e32 v107, v107
	s_waitcnt lgkmcnt(6)
	v_mfma_f32_32x32x16_bf16 v[32:47], v[64:67], v[214:217], v[32:47]
	ds_read_b64_tr_b16 v[214:215], v171 offset:0x2400
	ds_read_b64_tr_b16 v[216:217], v171 offset:0x2c00
	v_exp_f32_e32 v108, v108
	v_exp_f32_e32 v109, v109
	v_add_f32_e32 v172, 0, v96
	v_add_f32_e32 v172, v97, v172
	s_waitcnt lgkmcnt(6)
	v_mfma_f32_32x32x16_bf16 v[32:47], v[68:71], v[218:221], v[32:47]
	ds_read_b64_tr_b16 v[218:219], v171 offset:0x3400
	ds_read_b64_tr_b16 v[220:221], v171 offset:0x3c00
	v_exp_f32_e32 v110, v110
	v_exp_f32_e32 v111, v111
	v_add_f32_e32 v172, v98, v172
	v_add_f32_e32 v172, v99, v172
	s_waitcnt lgkmcnt(6)
	v_mfma_f32_32x32x16_bf16 v[16:31], v[130:133], v[72:75], v[16:31]
	ds_read_b64_tr_b16 v[72:73], v171 offset:0x600
	ds_read_b64_tr_b16 v[74:75], v171 offset:0xe00
	v_add_f32_e32 v172, v100, v172
	v_add_f32_e32 v172, v101, v172
	s_waitcnt lgkmcnt(6)
	v_mfma_f32_32x32x16_bf16 v[16:31], v[134:137], v[76:79], v[16:31]
	ds_read_b64_tr_b16 v[76:77], v171 offset:0x1600
	ds_read_b64_tr_b16 v[78:79], v171 offset:0x1e00
	v_add_f32_e32 v172, v102, v172
	v_add_f32_e32 v172, v103, v172
	s_waitcnt lgkmcnt(6)
	v_mfma_f32_32x32x16_bf16 v[16:31], v[64:67], v[214:217], v[16:31]
	ds_read_b64_tr_b16 v[214:215], v171 offset:0x2600
	ds_read_b64_tr_b16 v[216:217], v171 offset:0x2e00
	v_add_f32_e32 v172, v104, v172
	v_add_f32_e32 v172, v105, v172
	s_waitcnt lgkmcnt(6)
	v_mfma_f32_32x32x16_bf16 v[16:31], v[68:71], v[218:221], v[16:31]
	ds_read_b64_tr_b16 v[218:219], v171 offset:0x3600
	ds_read_b64_tr_b16 v[220:221], v171 offset:0x3e00
	v_add_f32_e32 v172, v106, v172
	v_add_f32_e32 v172, v107, v172
	s_waitcnt lgkmcnt(6)
	v_mfma_f32_32x32x16_bf16 v[0:15], v[130:133], v[72:75], v[0:15]
	v_add_f32_e32 v172, v108, v172
	v_add_f32_e32 v172, v109, v172
	v_cvt_pk_bf16_f32 v130, v96, v97
	v_cvt_pk_bf16_f32 v131, v98, v99
	v_cvt_pk_bf16_f32 v132, v100, v101
	v_cvt_pk_bf16_f32 v133, v102, v103
	s_waitcnt lgkmcnt(4)
	v_mfma_f32_32x32x16_bf16 v[0:15], v[134:137], v[76:79], v[0:15]
	v_add_f32_e32 v172, v110, v172
	v_add_f32_e32 v172, v111, v172
	v_cvt_pk_bf16_f32 v134, v104, v105
	v_cvt_pk_bf16_f32 v135, v106, v107
	v_cvt_pk_bf16_f32 v136, v108, v109
	v_cvt_pk_bf16_f32 v137, v110, v111
	v_permlane32_swap_b32_e32 v130, v132
	v_permlane32_swap_b32_e32 v131, v133
	s_waitcnt lgkmcnt(2)
	v_mfma_f32_32x32x16_bf16 v[0:15], v[64:67], v[214:217], v[0:15]
	v_permlane32_swap_b32_e32 v134, v136
	v_permlane32_swap_b32_e32 v135, v137
	s_waitcnt lgkmcnt(0)
	v_mfma_f32_32x32x16_bf16 v[0:15], v[68:71], v[218:221], v[0:15]
	s_waitcnt vmcnt(0)
	s_waitcnt lgkmcnt(0)
	s_barrier
; #define SBAR() __builtin_amdgcn_sched_barrier(0)
; #define SLOAD(i, k0) do { sr_[i].vs0 = *reinterpret_cast<const bf16x8*>(&Vh[(size_t)((k0) + sr) * ldk + sc]); sr_[i].vs1 = *reinterpret_cast<const bf16x8*>(&Vh[(size_t)((k0) + 32 + sr) * ldk + sc]); \
;     sr_[i].ks0 = *reinterpret_cast<const bf16x8*>(&Kh[(size_t)((k0) + sr) * ldk + sc]); sr_[i].ks1 = *reinterpret_cast<const bf16x8*>(&Kh[(size_t)((k0) + 32 + sr) * ldk + sc]); } while (0)
; DEVINL void partialSM_bal(f32x16& p0, float& ps, bf16x8& pa0, bf16x8& pa1) {
; #pragma unroll
;   for (int r = 0; r < 16; ++r) p0[r] = __builtin_amdgcn_exp2f(p0[r]);
;   float s = 0;
; #pragma unroll
;   for (int r = 0; r < 16; ++r) s += p0[r];
;   ps = s;
;   PK4F(p0, 0, pa0); PK4F(p0, 8, pa1);
; }
; DEVINL void finishSM_bal(f32x16& p1, float ps, float& l_reg, bf16x8& pa2, bf16x8& pa3) {
; #pragma unroll
;   for (int r = 0; r < 16; ++r) p1[r] = __builtin_amdgcn_exp2f(p1[r]);
; #pragma unroll
;   for (int r = 0; r < 16; ++r) ps += p1[r];
;   { auto rr = __builtin_amdgcn_permlane32_swap(__float_as_uint(ps), __float_as_uint(ps), false, false);
;     ps = __uint_as_float(rr[0]) + __uint_as_float(rr[1]); }
;   l_reg += ps;
;   PK4F(p1, 0, pa2); PK4F(p1, 8, pa3);
; }
; template <int ND0>
; DEVINL void qkt(f32x16& p0, f32x16& p1, const bf16* Ks, const bf16x8* qr, int r32, int hi, int colbase) {
;   p0 = f32x16{}; p1 = f32x16{};
;   __builtin_amdgcn_iglp_opt(1);
; #pragma unroll
;   for (int d0 = 0; d0 < ND0; ++d0) { int cb = (colbase + d0 * 16 + hi * 8) * 2;
;     bf16x8 b0 = *reinterpret_cast<const bf16x8*>((const char*)Ks + KSWZ(r32, cb));
;     bf16x8 b1 = *reinterpret_cast<const bf16x8*>((const char*)Ks + KSWZ(32 + r32, cb));
;     p0 = __builtin_amdgcn_mfma_f32_32x32x16_bf16(b0, qr[d0], p0, 0, 0, 0);
;     p1 = __builtin_amdgcn_mfma_f32_32x32x16_bf16(b1, qr[d0], p1, 0, 0, 0); }
; }
; template <bool DIFF, bool FAST> ...
;     ...
;     __syncthreads();
;     SBAR(); qkt<ND0>(pA0, pA1, K_lds, qr, r32, hi, colbase);
;     finishSM_bal(pB1, psB, l_reg, pa2, pa3); SBAR();
;     SLOAD(SE, (j + 3 < NT ? j + 3 : NT - 1) * KVBLK);     SBAR();
;     pv_d0(o, vb0 + (int)SHM_V, paB0, paB1, pa2, pa3); partialSM_bal(pA0, psA, paA0, paA1);
	ds_read_b128 v[64:67], v194 offset:32768
	ds_read_b128 v[68:71], v194 offset:40960
	ds_read_b128 v[138:141], v197 offset:32768
	ds_read_b128 v[142:145], v197 offset:40960
	ds_read_b128 v[146:149], v196 offset:32768
	ds_read_b128 v[214:217], v196 offset:40960
	ds_read_b128 v[218:221], v195 offset:32768
	ds_read_b128 v[222:225], v195 offset:40960
	s_add_i32 s9, s7, -1
	s_lshl_b32 s9, s9, 17
	s_add_u32 s10, s18, s9
	s_addc_u32 s11, s19, 0
	s_add_u32 m0, vcc_lo, vcc_hi
	s_add_u32 m0, m0, 0x4000
	s_nop 0
	global_load_lds_dwordx4 v184, s[10:11]
	v_exp_f32_e32 v80, v80
	v_exp_f32_e32 v83, v83
	v_exp_f32_e32 v84, v84
	v_exp_f32_e32 v85, v85
	s_waitcnt lgkmcnt(7)
	v_mfma_f32_32x32x16_bf16 v[96:111], v[64:67], v[126:129], 0
	s_add_u32 s10, s10, 0x10000
	s_addc_u32 s11, s11, 0
	s_add_u32 m0, m0, 0x2000
	s_nop 0
	global_load_lds_dwordx4 v184, s[10:11]
	v_exp_f32_e32 v86, v86
	v_exp_f32_e32 v87, v87
	v_exp_f32_e32 v88, v88
	v_exp_f32_e32 v89, v89
	s_waitcnt lgkmcnt(6)
	v_mfma_f32_32x32x16_bf16 v[64:79], v[68:71], v[126:129], 0
	s_add_u32 s10, s16, s9
	s_addc_u32 s11, s17, 0
	s_add_u32 m0, vcc_lo, 0xc000
	s_nop 0
	global_load_lds_dwordx4 v213, s[10:11]
	v_exp_f32_e32 v90, v90
	v_exp_f32_e32 v91, v91
	v_exp_f32_e32 v92, v92
	v_exp_f32_e32 v93, v93
	s_waitcnt lgkmcnt(5)
	v_mfma_f32_32x32x16_bf16 v[96:111], v[138:141], v[122:125], v[96:111]
	s_add_u32 s10, s10, 0x10000
	s_addc_u32 s11, s11, 0
	s_add_u32 m0, m0, 0x2000
	s_nop 0
	global_load_lds_dwordx4 v213, s[10:11]
	v_exp_f32_e32 v94, v94
	v_exp_f32_e32 v95, v95
	v_exp_f32_e32 v150, v81
	v_exp_f32_e32 v151, v82
	s_waitcnt lgkmcnt(4)
	v_mfma_f32_32x32x16_bf16 v[64:79], v[142:145], v[122:125], v[64:79]
	v_add_f32_e32 v81, v80, v172
	v_add_f32_e32 v81, v150, v81
	v_add_f32_e32 v81, v151, v81
	v_add_f32_e32 v81, v83, v81
	v_add_f32_e32 v81, v84, v81
	v_add_f32_e32 v81, v85, v81
	v_add_f32_e32 v81, v86, v81
	v_add_f32_e32 v81, v87, v81
	s_waitcnt lgkmcnt(3)
	v_mfma_f32_32x32x16_bf16 v[96:111], v[146:149], v[118:121], v[96:111]
	v_add_f32_e32 v81, v88, v81
	v_add_f32_e32 v81, v89, v81
	v_add_f32_e32 v81, v90, v81
	v_add_f32_e32 v81, v91, v81
	v_add_f32_e32 v81, v92, v81
	v_add_f32_e32 v81, v93, v81
	v_add_f32_e32 v81, v94, v81
	v_add_f32_e32 v81, v95, v81
	s_waitcnt lgkmcnt(2)
	v_mfma_f32_32x32x16_bf16 v[64:79], v[214:217], v[118:121], v[64:79]
	v_mov_b32_e32 v82, v81
	s_nop 1
	v_permlane32_swap_b32_e32 v81, v82
	v_add_f32_e32 v81, v81, v82
	v_cvt_pk_bf16_f32 v82, v80, v150
	v_cvt_pk_bf16_f32 v83, v151, v83
	v_cvt_pk_bf16_f32 v84, v84, v85
	v_cvt_pk_bf16_f32 v85, v86, v87
	s_waitcnt lgkmcnt(1)
	v_mfma_f32_32x32x16_bf16 v[96:111], v[218:221], v[114:117], v[96:111]
	v_cvt_pk_bf16_f32 v86, v88, v89
	v_cvt_pk_bf16_f32 v87, v90, v91
	v_cvt_pk_bf16_f32 v88, v92, v93
	v_cvt_pk_bf16_f32 v89, v94, v95
	v_permlane32_swap_b32_e32 v82, v84
	v_permlane32_swap_b32_e32 v83, v85
	v_permlane32_swap_b32_e32 v86, v88
	v_permlane32_swap_b32_e32 v87, v89
	s_waitcnt lgkmcnt(0)
	v_mfma_f32_32x32x16_bf16 v[64:79], v[222:225], v[114:117], v[64:79]
	ds_read_b64_tr_b16 v[90:91], v192 offset:0
	ds_read_b64_tr_b16 v[92:93], v192 offset:0x800
	ds_read_b64_tr_b16 v[214:215], v192 offset:0x1000
	ds_read_b64_tr_b16 v[216:217], v192 offset:0x1800
	ds_read_b64_tr_b16 v[218:219], v192 offset:0x2000
	ds_read_b64_tr_b16 v[220:221], v192 offset:0x2800
	ds_read_b64_tr_b16 v[222:223], v192 offset:0x3000
	ds_read_b64_tr_b16 v[224:225], v192 offset:0x3800
	s_waitcnt lgkmcnt(6)
	v_mfma_f32_32x32x16_bf16 v[48:63], v[130:133], v[90:93], v[48:63]
	ds_read_b64_tr_b16 v[90:91], v192 offset:0x200
	ds_read_b64_tr_b16 v[92:93], v192 offset:0xa00
	v_exp_f32_e32 v96, v96
	v_exp_f32_e32 v97, v97
	s_waitcnt lgkmcnt(6)
	v_mfma_f32_32x32x16_bf16 v[48:63], v[134:137], v[214:217], v[48:63]
	ds_read_b64_tr_b16 v[214:215], v192 offset:0x1200
	ds_read_b64_tr_b16 v[216:217], v192 offset:0x1a00
	v_exp_f32_e32 v98, v98
	v_exp_f32_e32 v99, v99

; #define SBAR() __builtin_amdgcn_sched_barrier(0)
; #define SLOAD(i, k0) do { sr_[i].vs0 = *reinterpret_cast<const bf16x8*>(&Vh[(size_t)((k0) + sr) * ldk + sc]); sr_[i].vs1 = *reinterpret_cast<const bf16x8*>(&Vh[(size_t)((k0) + 32 + sr) * ldk + sc]); \
;     sr_[i].ks0 = *reinterpret_cast<const bf16x8*>(&Kh[(size_t)((k0) + sr) * ldk + sc]); sr_[i].ks1 = *reinterpret_cast<const bf16x8*>(&Kh[(size_t)((k0) + 32 + sr) * ldk + sc]); } while (0)
; #define SWRITE(b, i) do { *(bf16x8*)((char*)V_lds + (b) * SHM_V + vst0) = sr_[i].vs0;          \
;     *(bf16x8*)((char*)V_lds + (b) * SHM_V + vst1) = sr_[i].vs1; int kc = sc * 2;               \
;     *(bf16x8*)((char*)K_lds + (b) * SHM_K + KSWZ(sr, kc)) = sr_[i].ks0;                       \
;     *(bf16x8*)((char*)K_lds + (b) * SHM_K + KSWZ(32 + sr, kc)) = sr_[i].ks1; } while (0)
; template <int OFF> DEVINL s16x4 tr_read(int vb) {
;   s16x4 r; asm volatile("ds_read_b64_tr_b16 %0, %1 offset:%2" : "=&v"(r) : "v"(vb), "i"(OFF) : "memory"); return r;
; }
; template <int D0> DEVINL void pv_one(f32x16& od, int vb, bf16x8 pa0, bf16x8 pa1, bf16x8 pa2, bf16x8 pa3) {
;   const s16x4 l0 = tr_read<v_rd_off(D0, 0, 0)>(vb), h0 = tr_read<v_rd_off(D0, 0, 1)>(vb), l1 = tr_read<v_rd_off(D0, 1, 0)>(vb), h1 = tr_read<v_rd_off(D0, 1, 1)>(vb);
;   const s16x4 l2 = tr_read<v_rd_off(D0, 2, 0)>(vb), h2 = tr_read<v_rd_off(D0, 2, 1)>(vb), l3 = tr_read<v_rd_off(D0, 3, 0)>(vb), h3 = tr_read<v_rd_off(D0, 3, 1)>(vb);
;   asm volatile("s_waitcnt lgkmcnt(0)" ::: "memory"); SBAR();
;     ...
;   od = __builtin_amdgcn_mfma_f32_32x32x16_bf16(pa0, PK(l0, h0), od, 0, 0, 0);
;   od = __builtin_amdgcn_mfma_f32_32x32x16_bf16(pa1, PK(l1, h1), od, 0, 0, 0);
;   od = __builtin_amdgcn_mfma_f32_32x32x16_bf16(pa2, PK(l2, h2), od, 0, 0, 0);
;   od = __builtin_amdgcn_mfma_f32_32x32x16_bf16(pa3, PK(l3, h3), od, 0, 0, 0);
;     ...
; }
; DEVINL void pv_d0(f32x16* o, int vb, bf16x8 pa0, bf16x8 pa1, bf16x8 pa2, bf16x8 pa3) {
;   pv_one<0>(o[0], vb, pa0, pa1, pa2, pa3); pv_one<1>(o[1], vb, pa0, pa1, pa2, pa3); pv_one<2>(o[2], vb, pa0, pa1, pa2, pa3); pv_one<3>(o[3], vb, pa0, pa1, pa2, pa3);
; }
; template <bool DIFF, bool FAST> ...
;     ...
;     SLOAD(SE, (j + 3 < NT ? j + 3 : NT - 1) * KVBLK);     SBAR();
;     pv_d0(o, vb0 + (int)SHM_V, paB0, paB1, pa2, pa3); partialSM_bal(pA0, psA, paA0, paA1);
;     __syncthreads(); SWAIT(); SWRITE(1, SO);
;     __syncthreads();
	s_waitcnt lgkmcnt(6)
	v_mfma_f32_32x32x16_bf16 v[48:63], v[82:85], v[218:221], v[48:63]
	ds_read_b64_tr_b16 v[218:219], v192 offset:0x2200
	ds_read_b64_tr_b16 v[220:221], v192 offset:0x2a00
	v_exp_f32_e32 v100, v100
	v_exp_f32_e32 v101, v101
	s_waitcnt lgkmcnt(6)
	v_mfma_f32_32x32x16_bf16 v[48:63], v[86:89], v[222:225], v[48:63]
	ds_read_b64_tr_b16 v[222:223], v192 offset:0x3200
	ds_read_b64_tr_b16 v[224:225], v192 offset:0x3a00
	v_exp_f32_e32 v102, v102
	v_exp_f32_e32 v103, v103
	s_waitcnt lgkmcnt(6)
	v_mfma_f32_32x32x16_bf16 v[32:47], v[130:133], v[90:93], v[32:47]
	ds_read_b64_tr_b16 v[90:91], v192 offset:0x400
	ds_read_b64_tr_b16 v[92:93], v192 offset:0xc00
	v_exp_f32_e32 v104, v104
	v_exp_f32_e32 v105, v105
	s_waitcnt lgkmcnt(6)
	v_mfma_f32_32x32x16_bf16 v[32:47], v[134:137], v[214:217], v[32:47]
	ds_read_b64_tr_b16 v[214:215], v192 offset:0x1400
	ds_read_b64_tr_b16 v[216:217], v192 offset:0x1c00
	v_exp_f32_e32 v106, v106
	v_exp_f32_e32 v107, v107
	s_waitcnt lgkmcnt(6)
	v_mfma_f32_32x32x16_bf16 v[32:47], v[82:85], v[218:221], v[32:47]
	ds_read_b64_tr_b16 v[218:219], v192 offset:0x2400
	ds_read_b64_tr_b16 v[220:221], v192 offset:0x2c00
	v_exp_f32_e32 v108, v108
	v_exp_f32_e32 v176, v109
	v_add_f32_e32 v174, 0, v96
	v_add_f32_e32 v174, v97, v174
	s_waitcnt lgkmcnt(6)
	v_mfma_f32_32x32x16_bf16 v[32:47], v[86:89], v[222:225], v[32:47]
	ds_read_b64_tr_b16 v[222:223], v192 offset:0x3400
	ds_read_b64_tr_b16 v[224:225], v192 offset:0x3c00
	v_exp_f32_e32 v172, v110
	v_exp_f32_e32 v80, v111
	v_add_f32_e32 v174, v98, v174
	v_add_f32_e32 v174, v99, v174
	s_waitcnt lgkmcnt(6)
	v_mfma_f32_32x32x16_bf16 v[16:31], v[130:133], v[90:93], v[16:31]
	ds_read_b64_tr_b16 v[90:91], v192 offset:0x600
	ds_read_b64_tr_b16 v[92:93], v192 offset:0xe00
	v_add_f32_e32 v174, v100, v174
	v_add_f32_e32 v174, v101, v174
	s_waitcnt lgkmcnt(6)
	v_mfma_f32_32x32x16_bf16 v[16:31], v[134:137], v[214:217], v[16:31]
	ds_read_b64_tr_b16 v[214:215], v192 offset:0x1600
	ds_read_b64_tr_b16 v[216:217], v192 offset:0x1e00
	v_add_f32_e32 v174, v102, v174
	v_add_f32_e32 v174, v103, v174
	s_waitcnt lgkmcnt(6)
	v_mfma_f32_32x32x16_bf16 v[16:31], v[82:85], v[218:221], v[16:31]
	ds_read_b64_tr_b16 v[218:219], v192 offset:0x2600
	ds_read_b64_tr_b16 v[220:221], v192 offset:0x2e00
	v_add_f32_e32 v174, v104, v174
	v_add_f32_e32 v174, v105, v174
	s_waitcnt lgkmcnt(6)
	v_mfma_f32_32x32x16_bf16 v[16:31], v[86:89], v[222:225], v[16:31]
	ds_read_b64_tr_b16 v[222:223], v192 offset:0x3600
	ds_read_b64_tr_b16 v[224:225], v192 offset:0x3e00
	v_add_f32_e32 v174, v106, v174
	v_add_f32_e32 v174, v107, v174
	s_waitcnt lgkmcnt(6)
	v_mfma_f32_32x32x16_bf16 v[0:15], v[130:133], v[90:93], v[0:15]
	v_add_f32_e32 v174, v108, v174
	v_cvt_pk_bf16_f32 v130, v96, v97
	v_cvt_pk_bf16_f32 v131, v98, v99
	v_cvt_pk_bf16_f32 v132, v100, v101
	v_cvt_pk_bf16_f32 v133, v102, v103
	s_waitcnt lgkmcnt(4)
	v_mfma_f32_32x32x16_bf16 v[0:15], v[134:137], v[214:217], v[0:15]
	v_cvt_pk_bf16_f32 v134, v104, v105
	v_cvt_pk_bf16_f32 v135, v106, v107
	v_cvt_pk_bf16_f32 v136, v108, v176
	v_cvt_pk_bf16_f32 v137, v172, v80
	v_permlane32_swap_b32_e32 v130, v132
	v_permlane32_swap_b32_e32 v131, v133
	s_waitcnt lgkmcnt(2)
	v_mfma_f32_32x32x16_bf16 v[0:15], v[82:85], v[218:221], v[0:15]
	v_permlane32_swap_b32_e32 v134, v136
	v_permlane32_swap_b32_e32 v135, v137
	v_pk_add_f32 v[82:83], v[176:177], v[174:175]
	v_pk_add_f32 v[82:83], v[172:173], v[82:83]
	v_pk_add_f32 v[174:175], v[80:81], v[82:83]
	v_xor_b32_e32 v171, 0x10000, v171
	v_xor_b32_e32 v192, 0x10000, v192
	s_xor_b32 vcc_hi, vcc_hi, 0x10000
	s_waitcnt lgkmcnt(0)
	v_mfma_f32_32x32x16_bf16 v[0:15], v[86:89], v[222:225], v[0:15]
	s_add_i32 s9, s7, 2
	s_add_i32 s7, s7, -1
	v_mov_b32_e32 v173, v175
	s_cmp_ge_i32 s7, s6
	s_mov_b32 s7, s9
	s_waitcnt vmcnt(0)
	s_waitcnt lgkmcnt(0)
	s_barrier
	s_cbranch_scc0 .Lattn_diff_top
	s_branch .LBB0_609
